# combo with flatter P6-end rank profile 5/5/4/4/4/4/3/3
# baseline (speedup 1.0000x reference)
; __global__ void __launch_bounds__(NTHREADS, 2) mk_fwd(Params P) {
;     ...
;     if (IN(7)) {
;         transpose_convert(lds, P.w_out + (size_t)2048 * 2048, WOUT1, 2048, 2048, G, bid);
;         transpose_convert(lds, P.w_gate + (size_t)2048 * 2048, WG1, 2048, 2048, G, bid);
;     }
.Ldyn7_nofetch:
	s_or_b64 exec, exec, s[18:19]
	s_waitcnt lgkmcnt(0)
	s_barrier
	ds_read_b32 v1, v46
	s_waitcnt lgkmcnt(0)
	v_readfirstlane_b32 s99, v1
	s_and_b32 s99, s99, 0xff
	s_and_b32 s101, s99, 1
	s_lshr_b32 s99, s99, 1
	s_lshr_b32 s4, s99, 4
	s_and_b32 s5, s99, 15
	s_mov_b32 s100, 5
	s_mov_b32 s99, 0
	s_cmp_lt_u32 s4, 1
	s_cbranch_scc1 .Lrk7_done
	s_mov_b32 s100, 5
	s_movk_i32 s99, 80
	s_cmp_lt_u32 s4, 2
	s_cbranch_scc1 .Lrk7_done
	s_mov_b32 s100, 4
	s_movk_i32 s99, 160
	s_cmp_lt_u32 s4, 3
	s_cbranch_scc1 .Lrk7_done
	s_mov_b32 s100, 4
	s_movk_i32 s99, 224
	s_cmp_lt_u32 s4, 4
	s_cbranch_scc1 .Lrk7_done
	s_mov_b32 s100, 4
	s_movk_i32 s99, 288
	s_cmp_lt_u32 s4, 5
	s_cbranch_scc1 .Lrk7_done
	s_mov_b32 s100, 4
	s_movk_i32 s99, 352
	s_cmp_lt_u32 s4, 6
	s_cbranch_scc1 .Lrk7_done
	s_mov_b32 s100, 3
	s_movk_i32 s99, 416
	s_cmp_lt_u32 s4, 7
	s_cbranch_scc1 .Lrk7_done
	s_mov_b32 s100, 3
	s_movk_i32 s99, 464
